# R1 ctx projection tiles handed to workgroups 160..183 (three v-path latent tiles) instead of 128..151 (three k-path tiles)
# speedup vs baseline: 1.0167x; 1.0046x over previous
; __device__ __forceinline__ bool tile_of(long Lidx, int nM, int nN, int& pm, int& pn) {
;     const int nwg = nM * nN; if (Lidx >= nwg) return false;
;     int wgid = (int)Lidx; { const int q = nwg / NXCD, r = nwg % NXCD, xcd = wgid % NXCD, off = wgid / NXCD; wgid = (xcd < r ? xcd * (q + 1) : r * (q + 1) + (xcd - r) * q) + off; }
;     const int nig = WGM * nN, gid = wgid / nig, fm = gid * WGM, gsz = (nM - fm) < WGM ? (nM - fm) : WGM;
;     pm = fm + ((wgid % nig) % gsz); pn = (wgid % nig) / gsz; return true;
; }
; __global__ void __launch_bounds__(512, 2) fwd_megakernel(Params Parg) {
;     ...
;           GridSched S{(const char*)(ws + WS_WIN + (size_t)1024 * D * 2), (const char*)(ws + WS_XN + (size_t)b * L * D * 2), D * 2, D * 2, 16, 12, L / 256, G, bid};
;           EpiProjT E; E.ktf = WSP(bf16_t, WS_KTQK); E.ktb = WSP(bf16_t, WS_KTQK + 32 * MiB); E.vt = WSP(bf16_t, WS_VT); E.dec = WSP(float, WS_DEC); E.ld = L; E.clen = CH; E.rope = 1; gemm_phase(lds, S, E); }
;         if (b == 0) { PHASE_BEGIN
;           GridSched S{(const char*)(ws + WS_WIN + (size_t)1024 * D * 2), (const char*)(ws + WS_XN + (size_t)T * D * 2), D * 2, D * 2, 16, 12, 2, G, (bid + 128) % G};
;           EpiProjT E; E.ktf = WSP(bf16_t, WS_CTX + CTX_KT); E.ktb = WSP(bf16_t, WS_CTX + CTX_KT + 512 * 1024); E.vt = WSP(bf16_t, WS_CTX + CTX_VT); E.dec = WSP(float, WS_DEC); E.ld = CTXL; E.clen = CTXL; E.rope = 0; gemm_phase(lds, S, E); }
.LBB0_474:
	s_or_b64 exec, exec, s[6:7]
	s_and_b32 s6, s28, 7
	s_mul_i32 s3, s29, s28
	s_mul_i32 s3, s3, s13
	s_cmpk_lt_i32 s2, 0x300
	v_writelane_b32 v254, s3, 10
	s_cselect_b64 s[4:5], -1, 0
	v_writelane_b32 v254, s4, 11
	s_ashr_i32 s3, s2, 31
	s_movk_i32 s13, 0x61
	v_writelane_b32 v254, s5, 12
	s_lshr_b32 s4, s3, 29
	s_add_i32 s4, s2, s4
	s_ashr_i32 s14, s4, 3
	s_and_b32 s4, s4, -8
	s_sub_i32 s12, s2, s4
	s_cmp_gt_i32 s12, -1
	s_cselect_b64 s[4:5], -1, 0
	v_writelane_b32 v254, s4, 13
	s_ashr_i32 s29, s28, 31
	s_add_i32 s8, s2, 0x60
	v_writelane_b32 v254, s5, 14
	s_ashr_i32 s4, s28, 3
	s_mul_i32 s4, s4, s12
	s_add_i32 s7, s4, s14
	s_ashr_i32 s4, s2, 1
	s_ashr_i32 s5, s4, 31
	s_lshl_b64 s[18:19], s[4:5], 19
	s_lshl_b32 s4, s2, 10
	s_add_i32 s9, s2, 64
	s_lshl_b32 s20, s28, 9
	s_lshl_b32 s10, s12, 6
	s_and_b32 s25, s4, 0x400
	s_cmp_lt_i32 s12, 0
	s_cselect_b64 s[4:5], -1, 0
	v_writelane_b32 v254, s4, 15
	s_mul_i32 s11, s12, 0x41
	s_mov_b32 s21, 0
	v_writelane_b32 v254, s5, 16
	s_and_b64 s[4:5], s[4:5], exec
	s_cselect_b32 s4, s13, 0x60
	s_mul_i32 s4, s12, s4
	s_cselect_b32 s10, s11, s10
	s_add_i32 s4, s4, s14
	s_ashr_i32 s5, s4, 31
	s_lshr_b32 s5, s5, 23
	s_add_i32 s5, s4, s5
	s_ashr_i32 s11, s5, 9
	s_and_b32 s5, s5, 0xfffffe00
	s_lshl_b32 s11, s11, 3
	v_writelane_b32 v254, s12, 17
	s_sub_i32 s12, s4, s5
	s_sub_i32 s4, 12, s11
	s_min_u32 s13, s4, 8
	s_cmp_eq_u32 s6, 0
	s_cselect_b32 s43, s7, s2
	s_cmpk_lt_i32 s43, 0x200
	s_cselect_b64 s[4:5], -1, 0
	v_writelane_b32 v254, s4, 18
	v_cvt_f32_ubyte0_e32 v1, s13
	s_waitcnt lgkmcnt(0)
	v_cvt_f32_i32_e32 v0, s12
	v_writelane_b32 v254, s5, 19
	s_ashr_i32 s5, s43, 2
	s_bfe_u32 s4, s43, 0x50002
	s_andn2_b32 s5, s5, 31
	s_or_b32 s6, s5, s4
	s_lshl_b32 s5, s43, 8
	s_lshl_b32 s4, s6, 9
	s_and_b32 s5, s5, 0x100
	s_or_b32 s4, s4, s5
	s_ashr_i32 s5, s4, 31
	s_lshl_b64 s[4:5], s[4:5], 10
	v_writelane_b32 v254, s4, 20
	s_bitcmp0_b32 s43, 1
	v_rcp_iflag_f32_e32 v2, v1
	v_writelane_b32 v254, s5, 21
	s_cselect_b64 s[4:5], -1, 0
	v_writelane_b32 v254, s4, 22
	v_mul_f32_e32 v2, v0, v2
	v_trunc_f32_e32 v2, v2
	v_writelane_b32 v254, s5, 23
	s_lshl_b32 s4, s6, 8
	s_ashr_i32 s5, s4, 31
	s_lshl_b64 s[4:5], s[4:5], 10
	v_writelane_b32 v254, s4, 24
	s_add_i32 s6, s10, s14
	v_fma_f32 v0, -v2, v1, v0
	v_writelane_b32 v254, s5, 25
	v_writelane_b32 v254, s14, 26
	s_ashr_i32 s4, s6, 31
	v_writelane_b32 v254, s4, 27
	s_lshr_b32 s4, s4, 26
	s_add_i32 s4, s6, s4
	s_ashr_i32 s5, s4, 6
	s_and_b32 s4, s4, 0xffc0
	v_writelane_b32 v254, s6, 28
	s_sub_i32 s6, s6, s4
	s_bfe_i32 s4, s6, 0x80000
	s_bfe_u32 s4, s4, 0x3000c
	s_add_i32 s7, s6, s4
	s_bfe_i32 s4, s7, 0x80000
	s_and_b32 s7, s7, 0xf8
	s_sub_i32 s6, s6, s7
	s_lshl_b32 s5, s5, 3
	s_sext_i32_i8 s6, s6
	s_add_i32 s6, s5, s6
	s_sext_i32_i16 s4, s4
	s_ashr_i32 s7, s6, 31
	s_lshr_b32 s4, s4, 3
	s_lshl_b64 s[6:7], s[6:7], 19
	v_writelane_b32 v254, s6, 29
	s_bfe_i64 s[4:5], s[4:5], 0x100000
	s_lshl_b64 s[4:5], s[4:5], 19
	v_writelane_b32 v254, s7, 30
	v_writelane_b32 v254, s4, 31
	v_cvt_i32_f32_e32 v2, v2
	v_writelane_b32 v255, s20, 0
	v_writelane_b32 v254, s5, 32
	s_ashr_i32 s4, s12, 30
	s_or_b32 s6, s4, 1
	v_cmp_ge_f32_e64 s[4:5], |v0|, v1
	s_and_b64 s[4:5], s[4:5], exec
	s_cselect_b32 s4, s6, 0
	s_abs_i32 s10, s28
	v_cvt_f32_u32_e32 v0, s10
	v_readfirstlane_b32 s5, v2
	s_add_i32 s4, s5, s4
	s_mul_i32 s5, s4, s13
	v_rcp_iflag_f32_e32 v0, v0
	s_sub_i32 s5, s12, s5
	s_sext_i32_i16 s5, s5
	s_add_i32 s6, s11, s5
	v_mul_f32_e32 v0, 0x4f7ffffe, v0
	v_cvt_u32_f32_e32 v0, v0
	s_ashr_i32 s7, s6, 31
	s_lshl_b64 s[6:7], s[6:7], 19
	v_writelane_b32 v254, s6, 33
	s_bfe_i64 s[4:5], s[4:5], 0x100000
	s_lshl_b64 s[4:5], s[4:5], 19
	v_writelane_b32 v254, s7, 34
	s_sub_i32 s6, 0, s10
	v_readfirstlane_b32 s7, v0
	s_mul_i32 s6, s6, s7
	v_writelane_b32 v254, s4, 35
	s_mul_hi_u32 s6, s7, s6
	s_add_i32 s7, s7, s6
	v_writelane_b32 v254, s5, 36
	s_abs_i32 s5, s8
	s_mul_hi_u32 s6, s5, s7
	s_mul_i32 s6, s6, s10
	s_sub_i32 s5, s5, s6
	s_ashr_i32 s4, s8, 31
	s_sub_i32 s6, s5, s10
	s_cmp_ge_u32 s5, s10
	s_cselect_b32 s5, s6, s5
	s_sub_i32 s6, s5, s10
	s_cmp_ge_u32 s5, s10
	s_cselect_b32 s5, s6, s5
	s_xor_b32 s5, s5, s4
	s_sub_i32 s12, s5, s4
	s_cmp_lt_i32 s12, 24
	s_cselect_b64 s[4:5], -1, 0
	v_writelane_b32 v254, s4, 37
	s_ashr_i32 s13, s12, 31
	s_mov_b32 s46, 0x20000
	v_writelane_b32 v254, s5, 38
	s_lshr_b32 s4, s13, 29
	s_add_i32 s4, s12, s4
	s_ashr_i32 s5, s4, 3
	v_writelane_b32 v254, s5, 39
	s_and_b32 s4, s4, -8
	v_writelane_b32 v254, s12, 40
	s_sub_i32 s4, s12, s4
	s_cmp_gt_i32 s4, -1
	v_writelane_b32 v254, s13, 41
	s_cselect_b64 s[12:13], -1, 0
	v_writelane_b32 v254, s12, 42
	s_mul_i32 s5, s4, 3
	s_lshl_b32 s4, s4, 2
	v_writelane_b32 v254, s13, 43
	v_writelane_b32 v254, s5, 44
	v_writelane_b32 v254, s4, 45
	s_abs_i32 s4, s9
	s_mul_hi_u32 s5, s4, s7
	s_mul_i32 s5, s5, s10
	s_sub_i32 s4, s4, s5
	s_ashr_i32 s6, s9, 31
	s_sub_i32 s5, s4, s10
	s_cmp_ge_u32 s4, s10
	s_cselect_b32 s4, s5, s4
	s_sub_i32 s5, s4, s10
	s_cmp_ge_u32 s4, s10
	s_cselect_b32 s4, s5, s4
	s_xor_b32 s7, s4, s6
	s_sub_i32 s9, s7, s6
	s_cmp_lt_i32 s9, 32
	s_cselect_b64 s[4:5], -1, 0
	v_writelane_b32 v254, s4, 46
	s_bfe_u32 s8, s9, 0x20002
	s_mov_b64 s[70:71], 0
	v_writelane_b32 v254, s5, 47
	s_ashr_i32 s4, s9, 4
	s_ashr_i32 s5, s4, 31
	s_lshl_b64 s[4:5], s[4:5], 23
	v_writelane_b32 v254, s4, 48
	v_mov_b32_e32 v129, 0
	v_mov_b32_e32 v156, 0x358637bd
	v_writelane_b32 v254, s5, 49
	s_lshl_b32 s5, s9, 17
	s_lshl_b32 s4, s8, 18
	s_and_b32 s5, s5, 0x20000
	s_or_b32 s4, s4, s5
	v_writelane_b32 v254, s4, 50
	s_bitcmp0_b32 s9, 1
	v_writelane_b32 v254, s9, 51
	s_cselect_b64 s[4:5], -1, 0
	v_writelane_b32 v254, s4, 52
	s_ashr_i32 s77, s76, 31
	s_lshl_b64 s[84:85], s[76:77], 11
	v_writelane_b32 v254, s5, 53
	s_lshl_b32 s4, s8, 17
	v_writelane_b32 v254, s4, 54
	s_mov_b32 s4, s76
	v_writelane_b32 v254, s4, 55
	v_writelane_b32 v255, s84, 1
	s_lshl_b64 s[86:87], s[76:77], 12
	v_writelane_b32 v254, s5, 56
	s_add_i32 s4, s28, s7
	s_sub_i32 s4, s4, s6
	v_writelane_b32 v254, s4, 57
	s_lshl_b32 s4, s4, 17
	v_writelane_b32 v254, s4, 58
	s_lshl_b32 s4, s28, 17
	v_writelane_b32 v254, s4, 59
	s_add_i32 s4, 0, 0x23000
	v_writelane_b32 v254, s4, 60
	s_add_i32 s4, 0, 0x23004
	v_writelane_b32 v254, s4, 61
	v_writelane_b32 v255, s85, 2
	v_writelane_b32 v254, s0, 62
	v_writelane_b32 v255, s86, 3
	s_mov_b32 s13, 0x800000
	s_mov_b32 s53, 0xebf00000
	s_movk_i32 s49, 0x1ff
	v_mov_b32_e32 v157, 1
	s_mov_b32 s60, 0x10000
	v_mov_b64_e32 v[250:251], 0x300
	v_mov_b64_e32 v[166:167], 0x2ff
	v_mov_b32_e32 v168, 0xf8
	v_mov_b32_e32 v252, 0xfffc0000
	v_mov_b32_e32 v169, 0x40000
	v_mov_b32_e32 v253, 0x3d800000
	s_mov_b64 s[72:73], -1
	v_writelane_b32 v254, s1, 63
	v_writelane_b32 v255, s87, 4
	s_barrier
	s_branch .LBB0_477
